# prologue tables moved to workgroups 192..255 (no layer-0 modulation item) from 0..63
# baseline (speedup 1.0000x reference)
.LBB0_33:
	v_readlane_b32 s4, v252, 7
	s_add_i32 s50, s95, 64
	s_and_b32 s50, s50, 0xff
	v_lshl_add_u32 v0, s50, 9, v16
	s_lshl_b32 s50, s4, 9
	s_movk_i32 s4, 0x2000
	v_cmp_gt_i32_e32 vcc, s4, v0
	v_ashrrev_i32_e32 v1, 31, v0
	s_and_saveexec_b64 s[4:5], vcc
	s_cbranch_execz .LBB0_36
	v_lshl_add_u64 v[2:3], v[0:1], 2, s[48:49]
	s_mov_b64 s[6:7], 0x180000
	s_ashr_i32 s51, s50, 31
	v_and_b32_e32 v4, 0x1ff, v16
	v_lshl_add_u64 v[2:3], v[2:3], 0, s[6:7]
	s_lshl_b64 s[6:7], s[50:51], 2
	s_mov_b64 s[52:53], 0
	s_movk_i32 s45, 0xfe00
	v_mov_b32_e32 v5, s43
	v_mov_b32_e32 v6, s39
	v_mov_b32_e32 v7, s42
	v_mov_b32_e32 v8, s38
	s_movk_i32 s38, 0x1fff
	v_mov_b32_e32 v9, v0
